# m0 write folded into s_add_i32 and hoisted above DMA address SALU in role-split attention loops (drops s_mov+s_nop per DMA)
# baseline (speedup 1.0000x reference)
.Lpqk2A:
	v_add_f32_e32 v230, v98, v99
	v_cvt_pk_bf16_f32 v150, v98, v99
	v_add_f32_e32 v231, v100, v101
	v_cvt_pk_bf16_f32 v151, v100, v101
	v_add_f32_e32 v230, v102, v230
	v_add_f32_e32 v231, v103, v231
	v_add_f32_e32 v230, v104, v230
	v_cvt_pk_bf16_f32 v152, v102, v103
	v_add_f32_e32 v231, v105, v231
	v_cvt_pk_bf16_f32 v153, v104, v105
	v_add_f32_e32 v230, v106, v230
	v_add_f32_e32 v231, v107, v231
	v_add_f32_e32 v230, v108, v230
	v_cvt_pk_bf16_f32 v10, v106, v107
	v_add_f32_e32 v231, v109, v231
	v_cvt_pk_bf16_f32 v11, v108, v109
	v_add_f32_e32 v230, v110, v230
	v_add_f32_e32 v231, v111, v231
	v_add_f32_e32 v230, v112, v230
	v_cvt_pk_bf16_f32 v12, v110, v111
	v_add_f32_e32 v231, v113, v231
	v_cvt_pk_bf16_f32 v13, v112, v113
	v_add_f32_e32 v230, v82, v230
	v_add_f32_e32 v231, v83, v231
	v_add_f32_e32 v230, v84, v230
	v_cvt_pk_bf16_f32 v6, v82, v83
	v_add_f32_e32 v231, v85, v231
	v_cvt_pk_bf16_f32 v7, v84, v85
	v_add_f32_e32 v230, v86, v230
	v_add_f32_e32 v231, v87, v231
	v_add_f32_e32 v230, v88, v230
	v_cvt_pk_bf16_f32 v8, v86, v87
	v_add_f32_e32 v231, v89, v231
	v_cvt_pk_bf16_f32 v9, v88, v89
	v_add_f32_e32 v230, v90, v230
	v_add_f32_e32 v231, v91, v231
	v_add_f32_e32 v230, v92, v230
	v_cvt_pk_bf16_f32 v2, v90, v91
	v_add_f32_e32 v231, v93, v231
	v_cvt_pk_bf16_f32 v3, v92, v93
	v_add_f32_e32 v230, v94, v230
	v_add_f32_e32 v231, v95, v231
	v_add_f32_e32 v230, v96, v230
	v_cvt_pk_bf16_f32 v4, v94, v95
	v_add_f32_e32 v231, v97, v231
	v_cvt_pk_bf16_f32 v5, v96, v97
	v_add_f32_e32 v230, v230, v231
	v_add_f32_e32 v206, v232, v230
	s_barrier
	s_setprio 1
	v_add_u32_e32 v0, s22, v251
	ds_read_b64_tr_b16 v[198:199], v0 offset:24576
	ds_read_b64_tr_b16 v[200:201], v0 offset:25088
	s_waitcnt lgkmcnt(9)
	v_mfma_f32_32x32x16_bf16 v[130:145], v[194:197], v[162:165], v[208:223]
	ds_read_b64_tr_b16 v[194:195], v0 offset:28672
	ds_read_b64_tr_b16 v[196:197], v0 offset:29184
	s_waitcnt lgkmcnt(10)
	v_mfma_f32_32x32x16_bf16 v[114:129], v[186:189], v[162:165], v[208:223]
	ds_read_b64_tr_b16 v[102:103], v0 offset:25600
	ds_read_b64_tr_b16 v[104:105], v0 offset:26112
	s_waitcnt lgkmcnt(11)
	v_mfma_f32_32x32x16_bf16 v[130:145], v[190:193], v[158:161], v[130:145]
	ds_read_b64_tr_b16 v[98:99], v0 offset:29696
	ds_read_b64_tr_b16 v[100:101], v0 offset:30208
	s_waitcnt lgkmcnt(12)
	v_mfma_f32_32x32x16_bf16 v[114:129], v[182:185], v[158:161], v[114:129]
	ds_read_b64_tr_b16 v[110:111], v0 offset:26624
	ds_read_b64_tr_b16 v[112:113], v0 offset:27136
	s_waitcnt lgkmcnt(13)
	v_mfma_f32_32x32x16_bf16 v[130:145], v[178:181], v[154:157], v[130:145]
	ds_read_b64_tr_b16 v[106:107], v0 offset:30720
	ds_read_b64_tr_b16 v[108:109], v0 offset:31232
	s_waitcnt lgkmcnt(14)
	v_mfma_f32_32x32x16_bf16 v[114:129], v[174:177], v[154:157], v[114:129]
	ds_read_b64_tr_b16 v[86:87], v0 offset:27648
	ds_read_b64_tr_b16 v[88:89], v0 offset:28160
	s_waitcnt lgkmcnt(14)
	v_mfma_f32_32x32x16_bf16 v[130:145], v[170:173], v[146:149], v[130:145]
	ds_read_b64_tr_b16 v[82:83], v0 offset:31744
	ds_read_b64_tr_b16 v[84:85], v0 offset:32256
	v_mfma_f32_32x32x16_bf16 v[114:129], v[166:169], v[146:149], v[114:129]
	s_add_i32 m0, s21, s43
	s_add_u32 s54, s48, s14
	s_addc_u32 s55, s49, s15
	s_add_u32 s56, s54, 0x8000
	s_addc_u32 s57, s55, 0
	global_load_lds_dwordx4 v202, s[56:57]
	s_add_i32 m0, s13, s44
	s_add_u32 s56, s50, s14
	s_addc_u32 s57, s51, s15
	s_add_u32 s56, s56, 0x4000
	s_addc_u32 s57, s57, 0
	global_load_lds_dwordx4 v203, s[56:57]
	s_add_i32 m0, s13, s45
	s_add_u32 s58, s52, s14
	s_addc_u32 s59, s53, s15
	s_add_u32 s58, s58, 0x4000
	s_addc_u32 s59, s59, 0
	global_load_lds_dwordx4 v203, s[58:59]
	v_add_u32_e32 v0, s22, v249
	v_add_u32_e32 v166, 0xe800, v0
	s_waitcnt lgkmcnt(14)
	v_mfma_f32_32x32x16_bf16 v[66:81], v[150:153], v[198:201], v[66:81]
	ds_read_b64_tr_b16 v[90:91], v0 offset:59392
	ds_read_b64_tr_b16 v[92:93], v0 offset:59904
	s_waitcnt lgkmcnt(14)
	v_mfma_f32_32x32x16_bf16 v[50:65], v[150:153], v[194:197], v[50:65]
	ds_read_b64_tr_b16 v[94:95], v0 offset:63488
	ds_read_b64_tr_b16 v[96:97], v0 offset:64000
	s_waitcnt lgkmcnt(14)
	v_mfma_f32_32x32x16_bf16 v[66:81], v[10:13], v[102:105], v[66:81]
	ds_read_b64_tr_b16 v[102:103], v0 offset:60416
	ds_read_b64_tr_b16 v[104:105], v0 offset:60928
	s_waitcnt lgkmcnt(14)
	v_mfma_f32_32x32x16_bf16 v[50:65], v[10:13], v[98:101], v[50:65]
	ds_read_b64_tr_b16 v[98:99], v0 offset:64512
	ds_read_b64_tr_b16 v[100:101], v0 offset:65024
	s_waitcnt lgkmcnt(14)
	v_mfma_f32_32x32x16_bf16 v[66:81], v[6:9], v[110:113], v[66:81]
	ds_read_b64_tr_b16 v[110:111], v0 offset:61440
	ds_read_b64_tr_b16 v[112:113], v0 offset:61952
	s_waitcnt lgkmcnt(14)
	v_mfma_f32_32x32x16_bf16 v[50:65], v[6:9], v[106:109], v[50:65]
	ds_read_b64_tr_b16 v[106:107], v166 offset:6144
	ds_read_b64_tr_b16 v[108:109], v166 offset:6656
	s_waitcnt lgkmcnt(14)
	v_mfma_f32_32x32x16_bf16 v[66:81], v[2:5], v[86:89], v[66:81]
	ds_read_b64_tr_b16 v[190:191], v0 offset:62464
	ds_read_b64_tr_b16 v[192:193], v0 offset:62976
	s_waitcnt lgkmcnt(14)
	v_mfma_f32_32x32x16_bf16 v[50:65], v[2:5], v[82:85], v[50:65]
	ds_read_b64_tr_b16 v[194:195], v166 offset:7168
	ds_read_b64_tr_b16 v[196:197], v166 offset:7680
	s_waitcnt lgkmcnt(14)
	v_mfma_f32_32x32x16_bf16 v[34:49], v[150:153], v[90:93], v[34:49]
	s_waitcnt lgkmcnt(12)
	v_mfma_f32_32x32x16_bf16 v[18:33], v[150:153], v[94:97], v[18:33]
	v_add_u32_e32 v0, s13, v250
	ds_read_b128 v[86:89], v0
	ds_read_b128 v[82:85], v0 offset:512
	s_waitcnt lgkmcnt(12)
	v_mfma_f32_32x32x16_bf16 v[34:49], v[10:13], v[102:105], v[34:49]
	ds_read_b128 v[186:189], v0 offset:2048
	ds_read_b128 v[182:185], v0 offset:2560
	s_waitcnt lgkmcnt(12)
	v_mfma_f32_32x32x16_bf16 v[18:33], v[10:13], v[98:101], v[18:33]
	ds_read_b128 v[178:181], v0 offset:4096
	ds_read_b128 v[174:177], v0 offset:4608
	s_waitcnt lgkmcnt(12)
	v_mfma_f32_32x32x16_bf16 v[34:49], v[6:9], v[110:113], v[34:49]
	ds_read_b128 v[170:173], v0 offset:6144
	ds_read_b128 v[166:169], v0 offset:6656
	s_waitcnt lgkmcnt(12)
	v_mfma_f32_32x32x16_bf16 v[18:33], v[6:9], v[106:109], v[18:33]
	s_waitcnt lgkmcnt(10)
	v_mfma_f32_32x32x16_bf16 v[34:49], v[2:5], v[190:193], v[34:49]
	s_waitcnt lgkmcnt(8)
	v_mfma_f32_32x32x16_bf16 v[18:33], v[2:5], v[194:197], v[18:33]
	s_setprio 0
	s_waitcnt vmcnt(3) lgkmcnt(0)
	s_barrier
	v_exp_f32_e32 v130, v130
	v_exp_f32_e32 v131, v131
	v_exp_f32_e32 v132, v132
	v_exp_f32_e32 v133, v133
	v_exp_f32_e32 v134, v134
	v_exp_f32_e32 v135, v135
	v_exp_f32_e32 v136, v136
	v_exp_f32_e32 v137, v137
	v_exp_f32_e32 v138, v138
	v_exp_f32_e32 v139, v139
	v_exp_f32_e32 v140, v140
	v_exp_f32_e32 v141, v141
	v_exp_f32_e32 v142, v142
	v_exp_f32_e32 v143, v143
	v_exp_f32_e32 v144, v144
	v_exp_f32_e32 v145, v145
	v_exp_f32_e32 v114, v114
	v_exp_f32_e32 v115, v115
	v_exp_f32_e32 v116, v116
	v_exp_f32_e32 v117, v117
	v_exp_f32_e32 v118, v118
	v_exp_f32_e32 v119, v119
	v_exp_f32_e32 v120, v120
	v_exp_f32_e32 v121, v121
	v_exp_f32_e32 v122, v122
	v_exp_f32_e32 v123, v123
	v_exp_f32_e32 v124, v124
	v_exp_f32_e32 v125, v125
	v_exp_f32_e32 v126, v126
	v_exp_f32_e32 v127, v127
	v_exp_f32_e32 v128, v128
	v_exp_f32_e32 v129, v129
	v_add_f32_e32 v230, v130, v131
	v_cvt_pk_bf16_f32 v150, v130, v131
	v_add_f32_e32 v231, v132, v133
	v_cvt_pk_bf16_f32 v151, v132, v133
	v_add_f32_e32 v230, v134, v230
	v_add_f32_e32 v231, v135, v231
	v_add_f32_e32 v230, v136, v230
	v_cvt_pk_bf16_f32 v152, v134, v135
	v_add_f32_e32 v231, v137, v231
	v_cvt_pk_bf16_f32 v153, v136, v137
	v_add_f32_e32 v230, v138, v230
	v_add_f32_e32 v231, v139, v231
	v_add_f32_e32 v230, v140, v230
	v_cvt_pk_bf16_f32 v10, v138, v139
	v_add_f32_e32 v231, v141, v231
	v_cvt_pk_bf16_f32 v11, v140, v141
	v_add_f32_e32 v230, v142, v230
	v_add_f32_e32 v231, v143, v231
	v_add_f32_e32 v230, v144, v230
	v_cvt_pk_bf16_f32 v12, v142, v143
	v_add_f32_e32 v231, v145, v231
	v_cvt_pk_bf16_f32 v13, v144, v145
	v_add_f32_e32 v230, v114, v230
	v_add_f32_e32 v231, v115, v231
	v_add_f32_e32 v230, v116, v230
	v_cvt_pk_bf16_f32 v6, v114, v115
	v_add_f32_e32 v231, v117, v231
	v_cvt_pk_bf16_f32 v7, v116, v117
	v_add_f32_e32 v230, v118, v230
	v_add_f32_e32 v231, v119, v231
	v_add_f32_e32 v230, v120, v230
	v_cvt_pk_bf16_f32 v8, v118, v119
	v_add_f32_e32 v231, v121, v231
	v_cvt_pk_bf16_f32 v9, v120, v121
	v_add_f32_e32 v230, v122, v230
	v_add_f32_e32 v231, v123, v231
	v_add_f32_e32 v230, v124, v230
	v_cvt_pk_bf16_f32 v2, v122, v123
	v_add_f32_e32 v231, v125, v231
	v_cvt_pk_bf16_f32 v3, v124, v125
	v_add_f32_e32 v230, v126, v230
	v_add_f32_e32 v231, v127, v231
	v_add_f32_e32 v230, v128, v230
	v_cvt_pk_bf16_f32 v4, v126, v127
	v_add_f32_e32 v231, v129, v231
	v_cvt_pk_bf16_f32 v5, v128, v129
	v_add_f32_e32 v230, v230, v231
	v_add_f32_e32 v232, v206, v230
	s_barrier
;   #define WB(a,b) do{ if constexpr(DV2){WAIT_BAR(b);} else {WAIT_BAR(a);} }while(0)
;   #define RESC() do{ if(resc){ asm volatile("s_waitcnt lgkmcnt(0)":::"memory"); \
;       _Pragma("unroll") for(int d_=0;d_<ND;++d_) _Pragma("unroll") for(int r=0;r<16;++r)o[d_][r]*=wsf[crow(r,hi)]; } }while(0)
;   #define ROT() do{sl_prev=sl_cur;sl_cur=sl_next;sl_next=(sl_next==(NSLOT-1)*SLOTB)?0:sl_next+SLOTB;}while(0)
;     ...
;   int t=1;
;   for(;t+5<NT;t+=2){
;     STEP(pB0,pB1,pA0,pA1,t,true,true,true);     WB(2,3); RESC(); ROT();
;     STEP(pA0,pA1,pB0,pB1,t+1,true,true,true);   WB(2,3); RESC(); ROT();
;   }
	s_setprio 1
	s_add_i32 s16, s13, 0x2000
	s_cmpk_lg_i32 s13, 0x4000
	s_cselect_b32 s47, s16, 0
	v_add_u32_e32 v207, s21, v251
	ds_read_b64_tr_b16 v[198:199], v207 offset:24576
	ds_read_b64_tr_b16 v[200:201], v207 offset:25088
	s_waitcnt lgkmcnt(9)
	v_mfma_f32_32x32x16_bf16 v[98:113], v[86:89], v[162:165], v[208:223]
	ds_read_b64_tr_b16 v[194:195], v207 offset:28672
	ds_read_b64_tr_b16 v[196:197], v207 offset:29184
	s_waitcnt lgkmcnt(10)
	v_mfma_f32_32x32x16_bf16 v[82:97], v[82:85], v[162:165], v[208:223]
	ds_read_b64_tr_b16 v[190:191], v207 offset:25600
	ds_read_b64_tr_b16 v[192:193], v207 offset:26112
	s_waitcnt lgkmcnt(11)
	v_mfma_f32_32x32x16_bf16 v[98:113], v[186:189], v[158:161], v[98:113]
	ds_read_b64_tr_b16 v[138:139], v207 offset:29696
	ds_read_b64_tr_b16 v[140:141], v207 offset:30208
	s_waitcnt lgkmcnt(12)
	v_mfma_f32_32x32x16_bf16 v[82:97], v[182:185], v[158:161], v[82:97]
	ds_read_b64_tr_b16 v[134:135], v207 offset:26624
	ds_read_b64_tr_b16 v[136:137], v207 offset:27136
	s_waitcnt lgkmcnt(13)
	v_mfma_f32_32x32x16_bf16 v[98:113], v[178:181], v[154:157], v[98:113]
	ds_read_b64_tr_b16 v[130:131], v207 offset:30720
	ds_read_b64_tr_b16 v[132:133], v207 offset:31232
	s_waitcnt lgkmcnt(14)
	v_mfma_f32_32x32x16_bf16 v[82:97], v[174:177], v[154:157], v[82:97]
	ds_read_b64_tr_b16 v[118:119], v207 offset:27648
	ds_read_b64_tr_b16 v[120:121], v207 offset:28160
	s_waitcnt lgkmcnt(14)
	v_mfma_f32_32x32x16_bf16 v[98:113], v[170:173], v[146:149], v[98:113]
	ds_read_b64_tr_b16 v[114:115], v207 offset:31744
	ds_read_b64_tr_b16 v[116:117], v207 offset:32256
	v_mfma_f32_32x32x16_bf16 v[82:97], v[166:169], v[146:149], v[82:97]
	s_add_i32 m0, s13, s43
	s_add_u32 s56, s54, 0xa000
	s_addc_u32 s57, s55, 0
	global_load_lds_dwordx4 v202, s[56:57]
	s_add_i32 m0, s47, s44
	s_add_u32 s56, s50, s14
	s_addc_u32 s57, s51, s15
	s_add_u32 s56, s56, 0x6000
	s_addc_u32 s57, s57, 0
	global_load_lds_dwordx4 v203, s[56:57]
	s_add_i32 m0, s47, s45
	s_add_u32 s58, s52, s14
	s_addc_u32 s59, s53, s15
	s_add_u32 s58, s58, 0x6000
	s_addc_u32 s59, s59, 0
	global_load_lds_dwordx4 v203, s[58:59]
	v_add_u32_e32 v14, s21, v249
	v_add_u32_e32 v15, 0xe800, v14
	s_waitcnt lgkmcnt(14)
	v_mfma_f32_32x32x16_bf16 v[66:81], v[150:153], v[198:201], v[66:81]
	ds_read_b64_tr_b16 v[122:123], v14 offset:59392
	ds_read_b64_tr_b16 v[124:125], v14 offset:59904
	s_waitcnt lgkmcnt(14)
	v_mfma_f32_32x32x16_bf16 v[50:65], v[150:153], v[194:197], v[50:65]
	ds_read_b64_tr_b16 v[126:127], v14 offset:63488
	ds_read_b64_tr_b16 v[128:129], v14 offset:64000
	s_waitcnt lgkmcnt(14)
	v_mfma_f32_32x32x16_bf16 v[66:81], v[10:13], v[190:193], v[66:81]
	ds_read_b64_tr_b16 v[142:143], v14 offset:60416
	ds_read_b64_tr_b16 v[144:145], v14 offset:60928
	s_waitcnt lgkmcnt(14)
	v_mfma_f32_32x32x16_bf16 v[50:65], v[10:13], v[138:141], v[50:65]
	ds_read_b64_tr_b16 v[138:139], v14 offset:64512
	ds_read_b64_tr_b16 v[140:141], v14 offset:65024
	s_waitcnt lgkmcnt(14)
	v_mfma_f32_32x32x16_bf16 v[66:81], v[6:9], v[134:137], v[66:81]
	ds_read_b64_tr_b16 v[134:135], v14 offset:61440
	ds_read_b64_tr_b16 v[136:137], v14 offset:61952
	s_waitcnt lgkmcnt(14)
	v_mfma_f32_32x32x16_bf16 v[50:65], v[6:9], v[130:133], v[50:65]
	ds_read_b64_tr_b16 v[130:131], v15 offset:6144
	ds_read_b64_tr_b16 v[132:133], v15 offset:6656
	s_waitcnt lgkmcnt(14)
	v_mfma_f32_32x32x16_bf16 v[66:81], v[2:5], v[118:121], v[66:81]
	ds_read_b64_tr_b16 v[118:119], v14 offset:62464
	ds_read_b64_tr_b16 v[120:121], v14 offset:62976
	s_waitcnt lgkmcnt(14)
	v_mfma_f32_32x32x16_bf16 v[50:65], v[2:5], v[114:117], v[50:65]
	ds_read_b64_tr_b16 v[114:115], v15 offset:7168
	ds_read_b64_tr_b16 v[116:117], v15 offset:7680
	s_waitcnt lgkmcnt(14)
	v_mfma_f32_32x32x16_bf16 v[34:49], v[150:153], v[122:125], v[34:49]
	s_waitcnt lgkmcnt(12)
	v_mfma_f32_32x32x16_bf16 v[18:33], v[150:153], v[126:129], v[18:33]
	v_add_u32_e32 v14, s47, v250
	ds_read_b128 v[194:197], v14
	ds_read_b128 v[186:189], v14 offset:512
	s_waitcnt lgkmcnt(12)
	v_mfma_f32_32x32x16_bf16 v[34:49], v[10:13], v[142:145], v[34:49]
	ds_read_b128 v[190:193], v14 offset:2048
	ds_read_b128 v[182:185], v14 offset:2560
	s_waitcnt lgkmcnt(12)
	v_mfma_f32_32x32x16_bf16 v[18:33], v[10:13], v[138:141], v[18:33]
	ds_read_b128 v[178:181], v14 offset:4096
	ds_read_b128 v[174:177], v14 offset:4608
	s_waitcnt lgkmcnt(12)
	v_mfma_f32_32x32x16_bf16 v[34:49], v[6:9], v[134:137], v[34:49]
	ds_read_b128 v[170:173], v14 offset:6144
	ds_read_b128 v[166:169], v14 offset:6656
	s_waitcnt lgkmcnt(12)
	v_mfma_f32_32x32x16_bf16 v[18:33], v[6:9], v[130:133], v[18:33]
	s_waitcnt lgkmcnt(10)
	v_mfma_f32_32x32x16_bf16 v[34:49], v[2:5], v[118:121], v[34:49]
	s_waitcnt lgkmcnt(8)
	v_mfma_f32_32x32x16_bf16 v[18:33], v[2:5], v[114:117], v[18:33]
	s_setprio 0
	s_waitcnt vmcnt(3) lgkmcnt(0)
	s_barrier
	v_exp_f32_e32 v98, v98
	v_exp_f32_e32 v99, v99
	v_exp_f32_e32 v100, v100
	v_exp_f32_e32 v101, v101
	v_exp_f32_e32 v102, v102
	v_exp_f32_e32 v103, v103
	v_exp_f32_e32 v104, v104
	v_exp_f32_e32 v105, v105
	v_exp_f32_e32 v106, v106
	v_exp_f32_e32 v107, v107
	v_exp_f32_e32 v108, v108
	v_exp_f32_e32 v109, v109
	v_exp_f32_e32 v110, v110
	v_exp_f32_e32 v111, v111
	v_exp_f32_e32 v112, v112
	v_exp_f32_e32 v113, v113
	v_exp_f32_e32 v82, v82
	v_exp_f32_e32 v83, v83
	v_exp_f32_e32 v84, v84
	v_exp_f32_e32 v85, v85
	v_exp_f32_e32 v86, v86
	v_exp_f32_e32 v87, v87
	v_exp_f32_e32 v88, v88
	v_exp_f32_e32 v89, v89
	v_exp_f32_e32 v90, v90
	v_exp_f32_e32 v91, v91
	v_exp_f32_e32 v92, v92
	v_exp_f32_e32 v93, v93
	v_exp_f32_e32 v94, v94
	v_exp_f32_e32 v95, v95
	v_exp_f32_e32 v96, v96
	v_exp_f32_e32 v97, v97
	s_add_i32 s16, s47, 0x2000
	s_cmpk_lg_i32 s47, 0x4000
	s_cselect_b32 s46, s16, 0
	s_add_i32 s16, s20, 2
	s_add_u32 s14, s14, 0x4000
	s_addc_u32 s15, s15, 0
	s_cmp_ge_u32 s16, s39
	s_cbranch_scc1 .Lpqk2A_exit
	s_mov_b32 s20, s16
	s_mov_b32 s22, s13
	s_mov_b32 s21, s47
	s_mov_b32 s13, s46
	s_branch .Lpqk2A

.Lpqk2B:
	v_add_f32_e32 v230, v98, v99
	v_cvt_pk_bf16_f32 v150, v98, v99
	v_add_f32_e32 v231, v100, v101
	v_cvt_pk_bf16_f32 v151, v100, v101
	v_add_f32_e32 v230, v102, v230
	v_add_f32_e32 v231, v103, v231
	v_add_f32_e32 v230, v104, v230
	v_cvt_pk_bf16_f32 v152, v102, v103
	v_add_f32_e32 v231, v105, v231
	v_cvt_pk_bf16_f32 v153, v104, v105
	v_add_f32_e32 v230, v106, v230
	v_add_f32_e32 v231, v107, v231
	v_add_f32_e32 v230, v108, v230
	v_cvt_pk_bf16_f32 v10, v106, v107
	v_add_f32_e32 v231, v109, v231
	v_cvt_pk_bf16_f32 v11, v108, v109
	v_add_f32_e32 v230, v110, v230
	v_add_f32_e32 v231, v111, v231
	v_add_f32_e32 v230, v112, v230
	v_cvt_pk_bf16_f32 v12, v110, v111
	v_add_f32_e32 v231, v113, v231
	v_cvt_pk_bf16_f32 v13, v112, v113
	v_add_f32_e32 v230, v82, v230
	v_add_f32_e32 v231, v83, v231
	v_add_f32_e32 v230, v84, v230
	v_cvt_pk_bf16_f32 v6, v82, v83
	v_add_f32_e32 v231, v85, v231
	v_cvt_pk_bf16_f32 v7, v84, v85
	v_add_f32_e32 v230, v86, v230
	v_add_f32_e32 v231, v87, v231
	v_add_f32_e32 v230, v88, v230
	v_cvt_pk_bf16_f32 v8, v86, v87
	v_add_f32_e32 v231, v89, v231
	v_cvt_pk_bf16_f32 v9, v88, v89
	v_add_f32_e32 v230, v90, v230
	v_add_f32_e32 v231, v91, v231
	v_add_f32_e32 v230, v92, v230
	v_cvt_pk_bf16_f32 v2, v90, v91
	v_add_f32_e32 v231, v93, v231
	v_cvt_pk_bf16_f32 v3, v92, v93
	v_add_f32_e32 v230, v94, v230
	v_add_f32_e32 v231, v95, v231
	v_add_f32_e32 v230, v96, v230
	v_cvt_pk_bf16_f32 v4, v94, v95
	v_add_f32_e32 v231, v97, v231
	v_cvt_pk_bf16_f32 v5, v96, v97
	v_add_f32_e32 v230, v230, v231
	v_add_f32_e32 v206, v232, v230
	s_add_i32 m0, s21, s43
	s_add_u32 s54, s48, s14
	s_addc_u32 s55, s49, s15
	s_add_u32 s56, s54, 0x8000
	s_addc_u32 s57, s55, 0
	global_load_lds_dwordx4 v202, s[56:57]
	s_add_i32 m0, s13, s44
	s_add_u32 s56, s50, s14
	s_addc_u32 s57, s51, s15
	s_add_u32 s56, s56, 0x4000
	s_addc_u32 s57, s57, 0
	global_load_lds_dwordx4 v203, s[56:57]
	s_add_i32 m0, s13, s45
	s_add_u32 s58, s52, s14
	s_addc_u32 s59, s53, s15
	s_add_u32 s58, s58, 0x4000
	s_addc_u32 s59, s59, 0
	global_load_lds_dwordx4 v203, s[58:59]
	s_barrier
	s_setprio 1
	v_add_u32_e32 v0, s22, v251
	ds_read_b64_tr_b16 v[198:199], v0 offset:24576
	ds_read_b64_tr_b16 v[200:201], v0 offset:25088
	s_waitcnt lgkmcnt(9)
	v_mfma_f32_32x32x16_bf16 v[130:145], v[194:197], v[162:165], v[208:223]
	ds_read_b64_tr_b16 v[194:195], v0 offset:28672
	ds_read_b64_tr_b16 v[196:197], v0 offset:29184
	s_waitcnt lgkmcnt(10)
	v_mfma_f32_32x32x16_bf16 v[114:129], v[186:189], v[162:165], v[208:223]
	ds_read_b64_tr_b16 v[102:103], v0 offset:25600
	ds_read_b64_tr_b16 v[104:105], v0 offset:26112
	s_waitcnt lgkmcnt(11)
	v_mfma_f32_32x32x16_bf16 v[130:145], v[190:193], v[158:161], v[130:145]
	ds_read_b64_tr_b16 v[98:99], v0 offset:29696
	ds_read_b64_tr_b16 v[100:101], v0 offset:30208
	s_waitcnt lgkmcnt(12)
	v_mfma_f32_32x32x16_bf16 v[114:129], v[182:185], v[158:161], v[114:129]
	ds_read_b64_tr_b16 v[110:111], v0 offset:26624
	ds_read_b64_tr_b16 v[112:113], v0 offset:27136
	s_waitcnt lgkmcnt(13)
	v_mfma_f32_32x32x16_bf16 v[130:145], v[178:181], v[154:157], v[130:145]
	ds_read_b64_tr_b16 v[106:107], v0 offset:30720
	ds_read_b64_tr_b16 v[108:109], v0 offset:31232
	s_waitcnt lgkmcnt(14)
	v_mfma_f32_32x32x16_bf16 v[114:129], v[174:177], v[154:157], v[114:129]
	ds_read_b64_tr_b16 v[86:87], v0 offset:27648
	ds_read_b64_tr_b16 v[88:89], v0 offset:28160
	s_waitcnt lgkmcnt(14)
	v_mfma_f32_32x32x16_bf16 v[130:145], v[170:173], v[146:149], v[130:145]
	ds_read_b64_tr_b16 v[82:83], v0 offset:31744
	ds_read_b64_tr_b16 v[84:85], v0 offset:32256
	v_mfma_f32_32x32x16_bf16 v[114:129], v[166:169], v[146:149], v[114:129]
	v_add_u32_e32 v0, s22, v249
	v_add_u32_e32 v166, 0xe800, v0
	s_waitcnt lgkmcnt(14)
	v_mfma_f32_32x32x16_bf16 v[66:81], v[150:153], v[198:201], v[66:81]
	ds_read_b64_tr_b16 v[90:91], v0 offset:59392
	ds_read_b64_tr_b16 v[92:93], v0 offset:59904
	s_waitcnt lgkmcnt(14)
	v_mfma_f32_32x32x16_bf16 v[50:65], v[150:153], v[194:197], v[50:65]
	ds_read_b64_tr_b16 v[94:95], v0 offset:63488
	ds_read_b64_tr_b16 v[96:97], v0 offset:64000
	s_waitcnt lgkmcnt(14)
	v_mfma_f32_32x32x16_bf16 v[66:81], v[10:13], v[102:105], v[66:81]
	ds_read_b64_tr_b16 v[102:103], v0 offset:60416
	ds_read_b64_tr_b16 v[104:105], v0 offset:60928
	s_waitcnt lgkmcnt(14)
	v_mfma_f32_32x32x16_bf16 v[50:65], v[10:13], v[98:101], v[50:65]
	ds_read_b64_tr_b16 v[98:99], v0 offset:64512
	ds_read_b64_tr_b16 v[100:101], v0 offset:65024
	s_waitcnt lgkmcnt(14)
	v_mfma_f32_32x32x16_bf16 v[66:81], v[6:9], v[110:113], v[66:81]
	ds_read_b64_tr_b16 v[110:111], v0 offset:61440
	ds_read_b64_tr_b16 v[112:113], v0 offset:61952
	s_waitcnt lgkmcnt(14)
	v_mfma_f32_32x32x16_bf16 v[50:65], v[6:9], v[106:109], v[50:65]
	ds_read_b64_tr_b16 v[106:107], v166 offset:6144
	ds_read_b64_tr_b16 v[108:109], v166 offset:6656
	s_waitcnt lgkmcnt(14)
	v_mfma_f32_32x32x16_bf16 v[66:81], v[2:5], v[86:89], v[66:81]
	ds_read_b64_tr_b16 v[190:191], v0 offset:62464
	ds_read_b64_tr_b16 v[192:193], v0 offset:62976
	s_waitcnt lgkmcnt(14)
	v_mfma_f32_32x32x16_bf16 v[50:65], v[2:5], v[82:85], v[50:65]
	ds_read_b64_tr_b16 v[194:195], v166 offset:7168
	ds_read_b64_tr_b16 v[196:197], v166 offset:7680
	s_waitcnt lgkmcnt(14)
	v_mfma_f32_32x32x16_bf16 v[34:49], v[150:153], v[90:93], v[34:49]
	s_waitcnt lgkmcnt(12)
	v_mfma_f32_32x32x16_bf16 v[18:33], v[150:153], v[94:97], v[18:33]
	v_add_u32_e32 v0, s13, v250
	ds_read_b128 v[86:89], v0
	ds_read_b128 v[82:85], v0 offset:512
	s_waitcnt lgkmcnt(12)
	v_mfma_f32_32x32x16_bf16 v[34:49], v[10:13], v[102:105], v[34:49]
	ds_read_b128 v[186:189], v0 offset:2048
	ds_read_b128 v[182:185], v0 offset:2560
	s_waitcnt lgkmcnt(12)
	v_mfma_f32_32x32x16_bf16 v[18:33], v[10:13], v[98:101], v[18:33]
	ds_read_b128 v[178:181], v0 offset:4096
	ds_read_b128 v[174:177], v0 offset:4608
	s_waitcnt lgkmcnt(12)
	v_mfma_f32_32x32x16_bf16 v[34:49], v[6:9], v[110:113], v[34:49]
	ds_read_b128 v[170:173], v0 offset:6144
	ds_read_b128 v[166:169], v0 offset:6656
	s_waitcnt lgkmcnt(12)
	v_mfma_f32_32x32x16_bf16 v[18:33], v[6:9], v[106:109], v[18:33]
	s_waitcnt lgkmcnt(10)
	v_mfma_f32_32x32x16_bf16 v[34:49], v[2:5], v[190:193], v[34:49]
	s_waitcnt lgkmcnt(8)
	v_mfma_f32_32x32x16_bf16 v[18:33], v[2:5], v[194:197], v[18:33]
	s_setprio 0
	s_waitcnt vmcnt(3) lgkmcnt(0)
	s_barrier
	v_exp_f32_e32 v130, v130
	v_exp_f32_e32 v131, v131
	v_exp_f32_e32 v132, v132
	v_exp_f32_e32 v133, v133
	v_exp_f32_e32 v134, v134
	v_exp_f32_e32 v135, v135
	v_exp_f32_e32 v136, v136
	v_exp_f32_e32 v137, v137
	v_exp_f32_e32 v138, v138
	v_exp_f32_e32 v139, v139
	v_exp_f32_e32 v140, v140
	v_exp_f32_e32 v141, v141
	v_exp_f32_e32 v142, v142
	v_exp_f32_e32 v143, v143
	v_exp_f32_e32 v144, v144
	v_exp_f32_e32 v145, v145
	v_exp_f32_e32 v114, v114
	v_exp_f32_e32 v115, v115
	v_exp_f32_e32 v116, v116
	v_exp_f32_e32 v117, v117
	v_exp_f32_e32 v118, v118
	v_exp_f32_e32 v119, v119
	v_exp_f32_e32 v120, v120
	v_exp_f32_e32 v121, v121
	v_exp_f32_e32 v122, v122
	v_exp_f32_e32 v123, v123
	v_exp_f32_e32 v124, v124
	v_exp_f32_e32 v125, v125
	v_exp_f32_e32 v126, v126
	v_exp_f32_e32 v127, v127
	v_exp_f32_e32 v128, v128
	v_exp_f32_e32 v129, v129
	v_add_f32_e32 v230, v130, v131
	v_cvt_pk_bf16_f32 v150, v130, v131
	v_add_f32_e32 v231, v132, v133
	v_cvt_pk_bf16_f32 v151, v132, v133
	v_add_f32_e32 v230, v134, v230
	v_add_f32_e32 v231, v135, v231
	v_add_f32_e32 v230, v136, v230
	v_cvt_pk_bf16_f32 v152, v134, v135
	v_add_f32_e32 v231, v137, v231
	v_cvt_pk_bf16_f32 v153, v136, v137
	v_add_f32_e32 v230, v138, v230
	v_add_f32_e32 v231, v139, v231
	v_add_f32_e32 v230, v140, v230
	v_cvt_pk_bf16_f32 v10, v138, v139
	v_add_f32_e32 v231, v141, v231
	v_cvt_pk_bf16_f32 v11, v140, v141
	v_add_f32_e32 v230, v142, v230
	v_add_f32_e32 v231, v143, v231
	v_add_f32_e32 v230, v144, v230
	v_cvt_pk_bf16_f32 v12, v142, v143
	v_add_f32_e32 v231, v145, v231
	v_cvt_pk_bf16_f32 v13, v144, v145
	v_add_f32_e32 v230, v114, v230
	v_add_f32_e32 v231, v115, v231
	v_add_f32_e32 v230, v116, v230
	v_cvt_pk_bf16_f32 v6, v114, v115
	v_add_f32_e32 v231, v117, v231
	v_cvt_pk_bf16_f32 v7, v116, v117
	v_add_f32_e32 v230, v118, v230
	v_add_f32_e32 v231, v119, v231
	v_add_f32_e32 v230, v120, v230
	v_cvt_pk_bf16_f32 v8, v118, v119
	v_add_f32_e32 v231, v121, v231
	v_cvt_pk_bf16_f32 v9, v120, v121
	v_add_f32_e32 v230, v122, v230
	v_add_f32_e32 v231, v123, v231
	v_add_f32_e32 v230, v124, v230
	v_cvt_pk_bf16_f32 v2, v122, v123
	v_add_f32_e32 v231, v125, v231
	v_cvt_pk_bf16_f32 v3, v124, v125
	v_add_f32_e32 v230, v126, v230
	v_add_f32_e32 v231, v127, v231
	v_add_f32_e32 v230, v128, v230
	v_cvt_pk_bf16_f32 v4, v126, v127
	v_add_f32_e32 v231, v129, v231
	v_cvt_pk_bf16_f32 v5, v128, v129
	v_add_f32_e32 v230, v230, v231
	v_add_f32_e32 v232, v206, v230
	s_add_i32 s16, s13, 0x2000
	s_cmpk_lg_i32 s13, 0x4000
	s_cselect_b32 s47, s16, 0
	s_add_i32 m0, s13, s43
	s_add_u32 s56, s54, 0xa000
	s_addc_u32 s57, s55, 0
	global_load_lds_dwordx4 v202, s[56:57]
	s_add_i32 m0, s47, s44
	s_add_u32 s56, s50, s14
	s_addc_u32 s57, s51, s15
	s_add_u32 s56, s56, 0x6000
	s_addc_u32 s57, s57, 0
	global_load_lds_dwordx4 v203, s[56:57]
	s_add_i32 m0, s47, s45
	s_add_u32 s58, s52, s14
	s_addc_u32 s59, s53, s15
	s_add_u32 s58, s58, 0x6000
	s_addc_u32 s59, s59, 0
	global_load_lds_dwordx4 v203, s[58:59]
	s_barrier
;   #define WB(a,b) do{ if constexpr(DV2){WAIT_BAR(b);} else {WAIT_BAR(a);} }while(0)
;   #define RESC() do{ if(resc){ asm volatile("s_waitcnt lgkmcnt(0)":::"memory"); \
;       _Pragma("unroll") for(int d_=0;d_<ND;++d_) _Pragma("unroll") for(int r=0;r<16;++r)o[d_][r]*=wsf[crow(r,hi)]; } }while(0)
;   #define ROT() do{sl_prev=sl_cur;sl_cur=sl_next;sl_next=(sl_next==(NSLOT-1)*SLOTB)?0:sl_next+SLOTB;}while(0)
;     ...
;   int t=1;
;   for(;t+5<NT;t+=2){
;     STEP(pB0,pB1,pA0,pA1,t,true,true,true);     WB(2,3); RESC(); ROT();
;     STEP(pA0,pA1,pB0,pB1,t+1,true,true,true);   WB(2,3); RESC(); ROT();
;   }
	s_setprio 1
	v_add_u32_e32 v207, s21, v251
	ds_read_b64_tr_b16 v[198:199], v207 offset:24576
	ds_read_b64_tr_b16 v[200:201], v207 offset:25088
	s_waitcnt lgkmcnt(9)
	v_mfma_f32_32x32x16_bf16 v[98:113], v[86:89], v[162:165], v[208:223]
	ds_read_b64_tr_b16 v[194:195], v207 offset:28672
	ds_read_b64_tr_b16 v[196:197], v207 offset:29184
	s_waitcnt lgkmcnt(10)
	v_mfma_f32_32x32x16_bf16 v[82:97], v[82:85], v[162:165], v[208:223]
	ds_read_b64_tr_b16 v[190:191], v207 offset:25600
	ds_read_b64_tr_b16 v[192:193], v207 offset:26112
	s_waitcnt lgkmcnt(11)
	v_mfma_f32_32x32x16_bf16 v[98:113], v[186:189], v[158:161], v[98:113]
	ds_read_b64_tr_b16 v[138:139], v207 offset:29696
	ds_read_b64_tr_b16 v[140:141], v207 offset:30208
	s_waitcnt lgkmcnt(12)
	v_mfma_f32_32x32x16_bf16 v[82:97], v[182:185], v[158:161], v[82:97]
	ds_read_b64_tr_b16 v[134:135], v207 offset:26624
	ds_read_b64_tr_b16 v[136:137], v207 offset:27136
	s_waitcnt lgkmcnt(13)
	v_mfma_f32_32x32x16_bf16 v[98:113], v[178:181], v[154:157], v[98:113]
	ds_read_b64_tr_b16 v[130:131], v207 offset:30720
	ds_read_b64_tr_b16 v[132:133], v207 offset:31232
	s_waitcnt lgkmcnt(14)
	v_mfma_f32_32x32x16_bf16 v[82:97], v[174:177], v[154:157], v[82:97]
	ds_read_b64_tr_b16 v[118:119], v207 offset:27648
	ds_read_b64_tr_b16 v[120:121], v207 offset:28160
	s_waitcnt lgkmcnt(14)
	v_mfma_f32_32x32x16_bf16 v[98:113], v[170:173], v[146:149], v[98:113]
	ds_read_b64_tr_b16 v[114:115], v207 offset:31744
	ds_read_b64_tr_b16 v[116:117], v207 offset:32256
	v_mfma_f32_32x32x16_bf16 v[82:97], v[166:169], v[146:149], v[82:97]
	v_add_u32_e32 v14, s21, v249
	v_add_u32_e32 v15, 0xe800, v14
	s_waitcnt lgkmcnt(14)
	v_mfma_f32_32x32x16_bf16 v[66:81], v[150:153], v[198:201], v[66:81]
	ds_read_b64_tr_b16 v[122:123], v14 offset:59392
	ds_read_b64_tr_b16 v[124:125], v14 offset:59904
	s_waitcnt lgkmcnt(14)
	v_mfma_f32_32x32x16_bf16 v[50:65], v[150:153], v[194:197], v[50:65]
	ds_read_b64_tr_b16 v[126:127], v14 offset:63488
	ds_read_b64_tr_b16 v[128:129], v14 offset:64000
	s_waitcnt lgkmcnt(14)
	v_mfma_f32_32x32x16_bf16 v[66:81], v[10:13], v[190:193], v[66:81]
	ds_read_b64_tr_b16 v[142:143], v14 offset:60416
	ds_read_b64_tr_b16 v[144:145], v14 offset:60928
	s_waitcnt lgkmcnt(14)
	v_mfma_f32_32x32x16_bf16 v[50:65], v[10:13], v[138:141], v[50:65]
	ds_read_b64_tr_b16 v[138:139], v14 offset:64512
	ds_read_b64_tr_b16 v[140:141], v14 offset:65024
	s_waitcnt lgkmcnt(14)
	v_mfma_f32_32x32x16_bf16 v[66:81], v[6:9], v[134:137], v[66:81]
	ds_read_b64_tr_b16 v[134:135], v14 offset:61440
	ds_read_b64_tr_b16 v[136:137], v14 offset:61952
	s_waitcnt lgkmcnt(14)
	v_mfma_f32_32x32x16_bf16 v[50:65], v[6:9], v[130:133], v[50:65]
	ds_read_b64_tr_b16 v[130:131], v15 offset:6144
	ds_read_b64_tr_b16 v[132:133], v15 offset:6656
	s_waitcnt lgkmcnt(14)
	v_mfma_f32_32x32x16_bf16 v[66:81], v[2:5], v[118:121], v[66:81]
	ds_read_b64_tr_b16 v[118:119], v14 offset:62464
	ds_read_b64_tr_b16 v[120:121], v14 offset:62976
	s_waitcnt lgkmcnt(14)
	v_mfma_f32_32x32x16_bf16 v[50:65], v[2:5], v[114:117], v[50:65]
	ds_read_b64_tr_b16 v[114:115], v15 offset:7168
	ds_read_b64_tr_b16 v[116:117], v15 offset:7680
	s_waitcnt lgkmcnt(14)
	v_mfma_f32_32x32x16_bf16 v[34:49], v[150:153], v[122:125], v[34:49]
	s_waitcnt lgkmcnt(12)
	v_mfma_f32_32x32x16_bf16 v[18:33], v[150:153], v[126:129], v[18:33]
	v_add_u32_e32 v14, s47, v250
	ds_read_b128 v[194:197], v14
	ds_read_b128 v[186:189], v14 offset:512
	s_waitcnt lgkmcnt(12)
	v_mfma_f32_32x32x16_bf16 v[34:49], v[10:13], v[142:145], v[34:49]
	ds_read_b128 v[190:193], v14 offset:2048
	ds_read_b128 v[182:185], v14 offset:2560
	s_waitcnt lgkmcnt(12)
	v_mfma_f32_32x32x16_bf16 v[18:33], v[10:13], v[138:141], v[18:33]
	ds_read_b128 v[178:181], v14 offset:4096
	ds_read_b128 v[174:177], v14 offset:4608
	s_waitcnt lgkmcnt(12)
	v_mfma_f32_32x32x16_bf16 v[34:49], v[6:9], v[134:137], v[34:49]
	ds_read_b128 v[170:173], v14 offset:6144
	ds_read_b128 v[166:169], v14 offset:6656
	s_waitcnt lgkmcnt(12)
	v_mfma_f32_32x32x16_bf16 v[18:33], v[6:9], v[130:133], v[18:33]
	s_waitcnt lgkmcnt(10)
	v_mfma_f32_32x32x16_bf16 v[34:49], v[2:5], v[118:121], v[34:49]
	s_waitcnt lgkmcnt(8)
	v_mfma_f32_32x32x16_bf16 v[18:33], v[2:5], v[114:117], v[18:33]
	s_setprio 0
	s_waitcnt vmcnt(3) lgkmcnt(0)
	s_barrier
	v_exp_f32_e32 v98, v98
	v_exp_f32_e32 v99, v99
	v_exp_f32_e32 v100, v100
	v_exp_f32_e32 v101, v101
	v_exp_f32_e32 v102, v102
	v_exp_f32_e32 v103, v103
	v_exp_f32_e32 v104, v104
	v_exp_f32_e32 v105, v105
	v_exp_f32_e32 v106, v106
	v_exp_f32_e32 v107, v107
	v_exp_f32_e32 v108, v108
	v_exp_f32_e32 v109, v109
	v_exp_f32_e32 v110, v110
	v_exp_f32_e32 v111, v111
	v_exp_f32_e32 v112, v112
	v_exp_f32_e32 v113, v113
	v_exp_f32_e32 v82, v82
	v_exp_f32_e32 v83, v83
	v_exp_f32_e32 v84, v84
	v_exp_f32_e32 v85, v85
	v_exp_f32_e32 v86, v86
	v_exp_f32_e32 v87, v87
	v_exp_f32_e32 v88, v88
	v_exp_f32_e32 v89, v89
	v_exp_f32_e32 v90, v90
	v_exp_f32_e32 v91, v91
	v_exp_f32_e32 v92, v92
	v_exp_f32_e32 v93, v93
	v_exp_f32_e32 v94, v94
	v_exp_f32_e32 v95, v95
	v_exp_f32_e32 v96, v96
	v_exp_f32_e32 v97, v97
	s_add_i32 s16, s47, 0x2000
	s_cmpk_lg_i32 s47, 0x4000
	s_cselect_b32 s46, s16, 0
	s_add_i32 s16, s20, 2
	s_add_u32 s14, s14, 0x4000
	s_addc_u32 s15, s15, 0
	s_cmp_ge_u32 s16, s39
	s_cbranch_scc1 .LBB0_281
	s_mov_b32 s20, s16
	s_mov_b32 s22, s13
	s_mov_b32 s21, s47
	s_mov_b32 s13, s46
	s_branch .Lpqk2B

.Lfsk0_840:
	v_add_f32_e32 v212, v82, v83
	v_cvt_pk_bf16_f32 v134, v82, v83
	v_add_f32_e32 v213, v84, v85
	v_cvt_pk_bf16_f32 v135, v84, v85
	v_add_f32_e32 v212, v86, v212
	v_add_f32_e32 v213, v87, v213
	v_add_f32_e32 v212, v88, v212
	v_cvt_pk_bf16_f32 v136, v86, v87
	v_add_f32_e32 v213, v89, v213
	v_cvt_pk_bf16_f32 v137, v88, v89
	v_add_f32_e32 v212, v90, v212
	v_add_f32_e32 v213, v91, v213
	v_add_f32_e32 v212, v92, v212
	v_cvt_pk_bf16_f32 v10, v90, v91
	v_add_f32_e32 v213, v93, v213
	v_cvt_pk_bf16_f32 v11, v92, v93
	v_add_f32_e32 v212, v94, v212
	v_add_f32_e32 v213, v95, v213
	v_add_f32_e32 v212, v96, v212
	v_cvt_pk_bf16_f32 v12, v94, v95
	v_add_f32_e32 v213, v97, v213
	v_cvt_pk_bf16_f32 v13, v96, v97
	v_add_f32_e32 v212, v66, v212
	v_add_f32_e32 v213, v67, v213
	v_add_f32_e32 v212, v68, v212
	v_cvt_pk_bf16_f32 v6, v66, v67
	v_add_f32_e32 v213, v69, v213
	v_cvt_pk_bf16_f32 v7, v68, v69
	v_add_f32_e32 v212, v70, v212
	v_add_f32_e32 v213, v71, v213
	v_add_f32_e32 v212, v72, v212
	v_cvt_pk_bf16_f32 v8, v70, v71
	v_add_f32_e32 v213, v73, v213
	v_cvt_pk_bf16_f32 v9, v72, v73
	v_add_f32_e32 v212, v74, v212
	v_add_f32_e32 v213, v75, v213
	v_add_f32_e32 v212, v76, v212
	v_cvt_pk_bf16_f32 v2, v74, v75
	v_add_f32_e32 v213, v77, v213
	v_cvt_pk_bf16_f32 v3, v76, v77
	v_add_f32_e32 v212, v78, v212
	v_add_f32_e32 v213, v79, v213
	v_add_f32_e32 v212, v80, v212
	v_cvt_pk_bf16_f32 v4, v78, v79
	v_add_f32_e32 v213, v81, v213
	v_cvt_pk_bf16_f32 v5, v80, v81
	v_add_f32_e32 v212, v212, v213
	v_add_f32_e32 v192, v206, v212
	s_barrier
	s_setprio 1
	v_add_u32_e32 v193, s8, v204
	ds_read_b64_tr_b16 v[182:183], v193 offset:24576
	ds_read_b64_tr_b16 v[184:185], v193 offset:25088
	s_waitcnt lgkmcnt(9)
	v_mfma_f32_32x32x16_bf16 v[114:129], v[178:181], v[146:149], v[50:65]
	ds_read_b64_tr_b16 v[178:179], v193 offset:28672
	ds_read_b64_tr_b16 v[180:181], v193 offset:29184
	s_waitcnt lgkmcnt(10)
	v_mfma_f32_32x32x16_bf16 v[98:113], v[174:177], v[146:149], v[50:65]
	ds_read_b64_tr_b16 v[82:83], v193 offset:25600
	ds_read_b64_tr_b16 v[84:85], v193 offset:26112
	s_waitcnt lgkmcnt(11)
	v_mfma_f32_32x32x16_bf16 v[114:129], v[170:173], v[142:145], v[114:129]
	ds_read_b64_tr_b16 v[86:87], v193 offset:29696
	ds_read_b64_tr_b16 v[88:89], v193 offset:30208
	s_waitcnt lgkmcnt(12)
	v_mfma_f32_32x32x16_bf16 v[98:113], v[166:169], v[142:145], v[98:113]
	ds_read_b64_tr_b16 v[90:91], v193 offset:26624
	ds_read_b64_tr_b16 v[92:93], v193 offset:27136
	s_waitcnt lgkmcnt(13)
	v_mfma_f32_32x32x16_bf16 v[114:129], v[162:165], v[138:141], v[114:129]
	ds_read_b64_tr_b16 v[66:67], v193 offset:30720
	ds_read_b64_tr_b16 v[68:69], v193 offset:31232
	s_waitcnt lgkmcnt(14)
	v_mfma_f32_32x32x16_bf16 v[98:113], v[158:161], v[138:141], v[98:113]
	ds_read_b64_tr_b16 v[70:71], v193 offset:27648
	ds_read_b64_tr_b16 v[72:73], v193 offset:28160
	s_waitcnt lgkmcnt(14)
	v_mfma_f32_32x32x16_bf16 v[114:129], v[154:157], v[130:133], v[114:129]
	ds_read_b64_tr_b16 v[74:75], v193 offset:31744
	ds_read_b64_tr_b16 v[76:77], v193 offset:32256
	v_mfma_f32_32x32x16_bf16 v[98:113], v[150:153], v[130:133], v[98:113]
	s_add_i32 m0, s16, s26
	s_add_u32 s38, s34, s52
	s_addc_u32 s39, s35, s53
	global_load_lds_dwordx4 v208, s[38:39]
	s_add_i32 m0, s14, s27
	s_add_u32 s40, s36, s52
	s_addc_u32 s41, s37, s53
	global_load_lds_dwordx4 v210, s[40:41]
	s_waitcnt lgkmcnt(14)
	v_mfma_f32_32x32x16_bf16 v[34:49], v[134:137], v[182:185], v[34:49]
	s_waitcnt lgkmcnt(12)
	v_mfma_f32_32x32x16_bf16 v[18:33], v[134:137], v[178:181], v[18:33]
	v_add_u32_e32 v94, s14, v203
	ds_read_b128 v[78:81], v94
	ds_read_b128 v[178:181], v94 offset:512
	s_waitcnt lgkmcnt(12)
	v_mfma_f32_32x32x16_bf16 v[34:49], v[10:13], v[82:85], v[34:49]
	ds_read_b128 v[182:185], v94 offset:2048
	ds_read_b128 v[174:177], v94 offset:2560
	s_waitcnt lgkmcnt(12)
	v_mfma_f32_32x32x16_bf16 v[18:33], v[10:13], v[86:89], v[18:33]
	ds_read_b128 v[170:173], v94 offset:4096
	ds_read_b128 v[166:169], v94 offset:4608
	s_waitcnt lgkmcnt(12)
	v_mfma_f32_32x32x16_bf16 v[34:49], v[6:9], v[90:93], v[34:49]
	ds_read_b128 v[162:165], v94 offset:6144
	ds_read_b128 v[158:161], v94 offset:6656
	s_waitcnt lgkmcnt(12)
	v_mfma_f32_32x32x16_bf16 v[18:33], v[6:9], v[66:69], v[18:33]
	s_waitcnt lgkmcnt(10)
	v_mfma_f32_32x32x16_bf16 v[34:49], v[2:5], v[70:73], v[34:49]
	s_waitcnt lgkmcnt(8)
	v_mfma_f32_32x32x16_bf16 v[18:33], v[2:5], v[74:77], v[18:33]
	s_setprio 0
	s_waitcnt vmcnt(2) lgkmcnt(0)
	s_barrier
;   #define WB(a,b) do{ if constexpr(DV2){WAIT_BAR(b);} else {WAIT_BAR(a);} }while(0)
;   #define RESC() do{ if(resc){ asm volatile("s_waitcnt lgkmcnt(0)":::"memory"); \
;       _Pragma("unroll") for(int d_=0;d_<ND;++d_) _Pragma("unroll") for(int r=0;r<16;++r)o[d_][r]*=wsf[crow(r,hi)]; } }while(0)
;   #define ROT() do{sl_prev=sl_cur;sl_cur=sl_next;sl_next=(sl_next==(NSLOT-1)*SLOTB)?0:sl_next+SLOTB;}while(0)
;     ...
;   int t=1;
;   for(;t+5<NT;t+=2){
;     STEP(pB0,pB1,pA0,pA1,t,true,true,true);     WB(2,3); RESC(); ROT();
;     STEP(pA0,pA1,pB0,pB1,t+1,true,true,true);   WB(2,3); RESC(); ROT();
;   }
	v_exp_f32_e32 v114, v114
	v_exp_f32_e32 v115, v115
	v_exp_f32_e32 v116, v116
	v_exp_f32_e32 v117, v117
	v_exp_f32_e32 v118, v118
	v_exp_f32_e32 v119, v119
	v_exp_f32_e32 v120, v120
	v_exp_f32_e32 v121, v121
	v_exp_f32_e32 v122, v122
	v_exp_f32_e32 v123, v123
	v_exp_f32_e32 v124, v124
	v_exp_f32_e32 v125, v125
	v_exp_f32_e32 v126, v126
	v_exp_f32_e32 v127, v127
	v_exp_f32_e32 v128, v128
	v_exp_f32_e32 v129, v129
	v_exp_f32_e32 v98, v98
	v_exp_f32_e32 v99, v99
	v_exp_f32_e32 v100, v100
	v_exp_f32_e32 v101, v101
	v_exp_f32_e32 v102, v102
	v_exp_f32_e32 v103, v103
	v_exp_f32_e32 v104, v104
	v_exp_f32_e32 v105, v105
	v_exp_f32_e32 v106, v106
	v_exp_f32_e32 v107, v107
	v_exp_f32_e32 v108, v108
	v_exp_f32_e32 v109, v109
	v_exp_f32_e32 v110, v110
	v_exp_f32_e32 v111, v111
	v_exp_f32_e32 v112, v112
	v_exp_f32_e32 v113, v113
	v_add_f32_e32 v212, v114, v115
	v_cvt_pk_bf16_f32 v134, v114, v115
	v_add_f32_e32 v213, v116, v117
	v_cvt_pk_bf16_f32 v135, v116, v117
	v_add_f32_e32 v212, v118, v212
	v_add_f32_e32 v213, v119, v213
	v_add_f32_e32 v212, v120, v212
	v_cvt_pk_bf16_f32 v136, v118, v119
	v_add_f32_e32 v213, v121, v213
	v_cvt_pk_bf16_f32 v137, v120, v121
	v_add_f32_e32 v212, v122, v212
	v_add_f32_e32 v213, v123, v213
	v_add_f32_e32 v212, v124, v212
	v_cvt_pk_bf16_f32 v10, v122, v123
	v_add_f32_e32 v213, v125, v213
	v_cvt_pk_bf16_f32 v11, v124, v125
	v_add_f32_e32 v212, v126, v212
	v_add_f32_e32 v213, v127, v213
	v_add_f32_e32 v212, v128, v212
	v_cvt_pk_bf16_f32 v12, v126, v127
	v_add_f32_e32 v213, v129, v213
	v_cvt_pk_bf16_f32 v13, v128, v129
	v_add_f32_e32 v212, v98, v212
	v_add_f32_e32 v213, v99, v213
	v_add_f32_e32 v212, v100, v212
	v_cvt_pk_bf16_f32 v6, v98, v99
	v_add_f32_e32 v213, v101, v213
	v_cvt_pk_bf16_f32 v7, v100, v101
	v_add_f32_e32 v212, v102, v212
	v_add_f32_e32 v213, v103, v213
	v_add_f32_e32 v212, v104, v212
	v_cvt_pk_bf16_f32 v8, v102, v103
	v_add_f32_e32 v213, v105, v213
	v_cvt_pk_bf16_f32 v9, v104, v105
	v_add_f32_e32 v212, v106, v212
	v_add_f32_e32 v213, v107, v213
	v_add_f32_e32 v212, v108, v212
	v_cvt_pk_bf16_f32 v2, v106, v107
	v_add_f32_e32 v213, v109, v213
	v_cvt_pk_bf16_f32 v3, v108, v109
	v_add_f32_e32 v212, v110, v212
	v_add_f32_e32 v213, v111, v213
	v_add_f32_e32 v212, v112, v212
	v_cvt_pk_bf16_f32 v4, v110, v111
	v_add_f32_e32 v213, v113, v213
	v_cvt_pk_bf16_f32 v5, v112, v113
	v_add_f32_e32 v212, v212, v213
	v_add_f32_e32 v206, v192, v212
	s_barrier
	s_setprio 1
	s_add_i32 s8, s14, 0x2000
	s_cmpk_lg_i32 s14, 0x4000
	s_cselect_b32 s28, s8, 0
	v_add_u32_e32 v194, s16, v204
	ds_read_b64_tr_b16 v[154:155], v194 offset:24576
	ds_read_b64_tr_b16 v[156:157], v194 offset:25088
	s_waitcnt lgkmcnt(9)
	v_mfma_f32_32x32x16_bf16 v[82:97], v[78:81], v[146:149], v[50:65]
	ds_read_b64_tr_b16 v[150:151], v194 offset:28672
	ds_read_b64_tr_b16 v[152:153], v194 offset:29184
	s_waitcnt lgkmcnt(10)
	v_mfma_f32_32x32x16_bf16 v[66:81], v[178:181], v[146:149], v[50:65]
	ds_read_b64_tr_b16 v[114:115], v194 offset:25600
	ds_read_b64_tr_b16 v[116:117], v194 offset:26112
	s_waitcnt lgkmcnt(11)
	v_mfma_f32_32x32x16_bf16 v[82:97], v[182:185], v[142:145], v[82:97]
	ds_read_b64_tr_b16 v[118:119], v194 offset:29696
	ds_read_b64_tr_b16 v[120:121], v194 offset:30208
	s_waitcnt lgkmcnt(12)
	v_mfma_f32_32x32x16_bf16 v[66:81], v[174:177], v[142:145], v[66:81]
	ds_read_b64_tr_b16 v[122:123], v194 offset:26624
	ds_read_b64_tr_b16 v[124:125], v194 offset:27136
	s_waitcnt lgkmcnt(13)
	v_mfma_f32_32x32x16_bf16 v[82:97], v[170:173], v[138:141], v[82:97]
	ds_read_b64_tr_b16 v[98:99], v194 offset:30720
	ds_read_b64_tr_b16 v[100:101], v194 offset:31232
	s_waitcnt lgkmcnt(14)
	v_mfma_f32_32x32x16_bf16 v[66:81], v[166:169], v[138:141], v[66:81]
	ds_read_b64_tr_b16 v[102:103], v194 offset:27648
	ds_read_b64_tr_b16 v[104:105], v194 offset:28160
	s_waitcnt lgkmcnt(14)
	v_mfma_f32_32x32x16_bf16 v[82:97], v[162:165], v[130:133], v[82:97]
	ds_read_b64_tr_b16 v[106:107], v194 offset:31744
	ds_read_b64_tr_b16 v[108:109], v194 offset:32256
	v_mfma_f32_32x32x16_bf16 v[66:81], v[158:161], v[130:133], v[66:81]
	s_add_i32 m0, s14, s26
	s_nop 0
	global_load_lds_dwordx4 v208, s[34:35]
	s_add_i32 m0, s28, s27
	s_nop 0
	global_load_lds_dwordx4 v210, s[36:37]
	s_waitcnt lgkmcnt(14)
	v_mfma_f32_32x32x16_bf16 v[34:49], v[134:137], v[154:157], v[34:49]
	s_waitcnt lgkmcnt(12)
	v_mfma_f32_32x32x16_bf16 v[18:33], v[134:137], v[150:153], v[18:33]
	v_add_u32_e32 v110, s28, v203
	ds_read_b128 v[178:181], v110
	ds_read_b128 v[174:177], v110 offset:512
	s_waitcnt lgkmcnt(12)
	v_mfma_f32_32x32x16_bf16 v[34:49], v[10:13], v[114:117], v[34:49]
	ds_read_b128 v[170:173], v110 offset:2048
	ds_read_b128 v[166:169], v110 offset:2560
	s_waitcnt lgkmcnt(12)
	v_mfma_f32_32x32x16_bf16 v[18:33], v[10:13], v[118:121], v[18:33]
	ds_read_b128 v[162:165], v110 offset:4096
	ds_read_b128 v[158:161], v110 offset:4608
	s_waitcnt lgkmcnt(12)
	v_mfma_f32_32x32x16_bf16 v[34:49], v[6:9], v[122:125], v[34:49]
	ds_read_b128 v[154:157], v110 offset:6144
	ds_read_b128 v[150:153], v110 offset:6656
	s_waitcnt lgkmcnt(12)
	v_mfma_f32_32x32x16_bf16 v[18:33], v[6:9], v[98:101], v[18:33]
	s_waitcnt lgkmcnt(10)
	v_mfma_f32_32x32x16_bf16 v[34:49], v[2:5], v[102:105], v[34:49]
	s_waitcnt lgkmcnt(8)
	v_mfma_f32_32x32x16_bf16 v[18:33], v[2:5], v[106:109], v[18:33]
	s_setprio 0
	s_waitcnt vmcnt(2) lgkmcnt(0)
	s_barrier
	v_exp_f32_e32 v82, v82
	v_exp_f32_e32 v83, v83
	v_exp_f32_e32 v84, v84
	v_exp_f32_e32 v85, v85
	v_exp_f32_e32 v86, v86
	v_exp_f32_e32 v87, v87
	v_exp_f32_e32 v88, v88
	v_exp_f32_e32 v89, v89
	v_exp_f32_e32 v90, v90
	v_exp_f32_e32 v91, v91
	v_exp_f32_e32 v92, v92
	v_exp_f32_e32 v93, v93
	v_exp_f32_e32 v94, v94
	v_exp_f32_e32 v95, v95
	v_exp_f32_e32 v96, v96
	v_exp_f32_e32 v97, v97
	v_exp_f32_e32 v66, v66
	v_exp_f32_e32 v67, v67
	v_exp_f32_e32 v68, v68
	v_exp_f32_e32 v69, v69
	v_exp_f32_e32 v70, v70
	v_exp_f32_e32 v71, v71
	v_exp_f32_e32 v72, v72
	v_exp_f32_e32 v73, v73
	v_exp_f32_e32 v74, v74
	v_exp_f32_e32 v75, v75
	v_exp_f32_e32 v76, v76
	v_exp_f32_e32 v77, v77
	v_exp_f32_e32 v78, v78
	v_exp_f32_e32 v79, v79
	v_exp_f32_e32 v80, v80
	v_exp_f32_e32 v81, v81
	s_add_i32 s8, s28, 0x2000
	s_cmpk_lg_i32 s28, 0x4000
	s_cselect_b32 s29, s8, 0
	s_add_i32 s8, s15, 2
	s_add_u32 s36, s36, 0x4000
	s_addc_u32 s37, s37, 0
	s_add_u32 s34, s34, 0x4000
	s_addc_u32 s35, s35, 0
	s_cmp_ge_u32 s8, s25
	s_cbranch_scc1 .Lppk0_exit
	s_mov_b32 s15, s8
	s_mov_b32 s8, s14
	s_mov_b32 s16, s28
	s_mov_b32 s14, s29
	s_branch .Lfsk0_840
